# FFN hidden activation (SwiGLU epilogue) stores marked nt so the 184 MB stream does not displace the residual stream in the cache hierarchy
# baseline (speedup 1.0000x reference)
.LBB0_1087:
	v_mov_b32_e32 v188, v179
	s_lshl_b32 s0, s8, 8
	v_readfirstlane_b32 s2, v188
	s_ashr_i32 s1, s2, 2
	s_andn2_b32 s1, s1, 63
	s_add_i32 s1, s1, s0
	v_and_or_b32 v184, v188, 15, s1
	v_ashrrev_i32_e32 v185, 31, v184
	v_or_b32_e32 v170, 16, v184
	v_lshl_add_u64 v[128:129], v[184:185], 4, s[24:25]
	v_ashrrev_i32_e32 v171, 31, v170
	global_load_dwordx4 v[190:193], v[128:129], off
	v_lshl_add_u64 v[128:129], v[170:171], 4, s[24:25]
	global_load_dwordx4 v[194:197], v[128:129], off
	v_or_b32_e32 v166, 32, v184
	v_ashrrev_i32_e32 v167, 31, v166
	v_or_b32_e32 v164, 48, v184
	v_lshl_add_u64 v[128:129], v[166:167], 4, s[24:25]
	v_ashrrev_i32_e32 v165, 31, v164
	global_load_dwordx4 v[198:201], v[128:129], off
	v_lshl_add_u64 v[128:129], v[164:165], 4, s[24:25]
	global_load_dwordx4 v[214:217], v[128:129], off
	v_add_u32_e32 v162, 0x80, v184
	v_ashrrev_i32_e32 v163, 31, v162
	v_add_u32_e32 v160, 0x90, v184
	v_lshl_add_u64 v[128:129], v[162:163], 4, s[24:25]
	v_ashrrev_i32_e32 v161, 31, v160
	global_load_dwordx4 v[140:143], v[128:129], off
	v_lshl_add_u64 v[128:129], v[160:161], 4, s[24:25]
	v_add_u32_e32 v158, 0xa0, v184
	global_load_dwordx4 v[136:139], v[128:129], off
	v_ashrrev_i32_e32 v159, 31, v158
	v_add_u32_e32 v156, 0xb0, v184
	v_lshl_add_u64 v[128:129], v[158:159], 4, s[24:25]
	v_ashrrev_i32_e32 v157, 31, v156
	global_load_dwordx4 v[132:135], v[128:129], off
	v_lshl_add_u64 v[128:129], v[156:157], 4, s[24:25]
	global_load_dwordx4 v[128:131], v[128:129], off
	s_mov_b32 s0, 0x358637bd
	s_movk_i32 s8, 0x1600
	s_and_b32 s94, s2, 0xc0
	s_waitcnt vmcnt(0)
	v_mov_b32_e32 v186, v191
	v_mov_b32_e32 v187, v192
	v_mov_b32_e32 v191, v193
	v_pk_add_f32 v[186:187], v[186:187], v[190:191]
	v_mov_b32_e32 v190, v195
	v_mov_b32_e32 v191, v196
	v_mov_b32_e32 v195, v197
	v_pk_add_f32 v[190:191], v[190:191], v[194:195]
	v_mov_b32_e32 v193, v186
	v_mov_b32_e32 v192, v190
	v_mov_b32_e32 v186, v191
	v_pk_add_f32 v[190:191], v[192:193], v[186:187]
	v_mov_b64_e32 v[186:187], s[0:1]
	s_mov_b32 s0, 0x3a800000
	v_pk_fma_f32 v[190:191], v[190:191], s[0:1], v[186:187] op_sel_hi:[1,0,0]
	v_mov_b32_e32 v192, v215
	v_mul_f32_e32 v157, 0x4b800000, v191
	v_cmp_gt_f32_e64 s[4:5], s10, v191
	v_cmp_gt_f32_e32 vcc, s10, v190
	v_mov_b32_e32 v193, v216
	v_cndmask_b32_e64 v157, v191, v157, s[4:5]
	v_rsq_f32_e32 v157, v157
	v_mov_b32_e32 v191, v200
	v_mov_b32_e32 v215, v217
	v_pk_add_f32 v[192:193], v[192:193], v[214:215]
	v_mul_f32_e32 v159, 0x45800000, v157
	v_cndmask_b32_e64 v176, v157, v159, s[4:5]
	v_mul_f32_e32 v157, 0x4b800000, v190
	v_cndmask_b32_e32 v157, v190, v157, vcc
	v_rsq_f32_e32 v157, v157
	v_mov_b32_e32 v190, v199
	v_mov_b32_e32 v199, v201
	v_pk_add_f32 v[190:191], v[190:191], v[198:199]
	v_mov_b32_e32 v194, v192
	v_mov_b32_e32 v195, v190
	v_mov_b32_e32 v190, v193
	v_pk_add_f32 v[190:191], v[194:195], v[190:191]
	v_mul_f32_e32 v159, 0x45800000, v157
	v_pk_fma_f32 v[190:191], v[190:191], s[0:1], v[186:187] op_sel_hi:[1,0,0]
	v_cndmask_b32_e32 v174, v157, v159, vcc
	v_mul_f32_e32 v157, 0x4b800000, v191
	v_cmp_gt_f32_e64 s[4:5], s10, v191
	v_cmp_gt_f32_e32 vcc, s10, v190
	s_nop 0
	v_cndmask_b32_e64 v157, v191, v157, s[4:5]
	v_rsq_f32_e32 v157, v157
	v_mov_b32_e32 v191, v142
	v_mov_b32_e32 v142, v137
	v_mov_b32_e32 v137, v139
	v_mul_f32_e32 v159, 0x45800000, v157
	v_cndmask_b32_e64 v172, v157, v159, s[4:5]
	v_mul_f32_e32 v157, 0x4b800000, v190
	v_cndmask_b32_e32 v157, v190, v157, vcc
	v_mov_b32_e32 v190, v141
	v_mov_b32_e32 v141, v143
	v_mov_b32_e32 v143, v138
	v_pk_add_f32 v[140:141], v[190:191], v[140:141]
	v_pk_add_f32 v[136:137], v[142:143], v[136:137]
	v_mov_b32_e32 v139, v140
	v_mov_b32_e32 v138, v136
	v_mov_b32_e32 v140, v137
	v_pk_add_f32 v[136:137], v[138:139], v[140:141]
	v_mov_b32_e32 v140, v133
	v_mov_b32_e32 v141, v134
	v_mov_b32_e32 v133, v135
	v_mov_b32_e32 v134, v129
	v_mov_b32_e32 v135, v130
	v_mov_b32_e32 v129, v131
	v_pk_add_f32 v[132:133], v[140:141], v[132:133]
	v_pk_add_f32 v[128:129], v[134:135], v[128:129]
	v_mov_b32_e32 v131, v132
	v_mov_b32_e32 v130, v128
	v_mov_b32_e32 v132, v129
	v_pk_add_f32 v[128:129], v[130:131], v[132:133]
	v_mov_b32_e32 v132, v124
	v_mov_b32_e32 v133, v120
	v_pk_mul_f32 v[132:133], v[132:133], v[176:177] op_sel_hi:[1,0]
	v_pk_fma_f32 v[136:137], v[136:137], s[0:1], v[186:187] op_sel_hi:[1,0,0]
	v_mul_f32_e32 v124, 0xbfb8aa3b, v132
	v_exp_f32_e32 v124, v124
	v_mul_f32_e32 v120, v132, v133
	v_mul_f32_e32 v138, 0x4b800000, v137
	v_cmp_gt_f32_e64 s[4:5], s10, v137
	v_add_f32_e32 v124, 1.0, v124
	v_rcp_f32_e32 v124, v124
	v_cndmask_b32_e64 v137, v137, v138, s[4:5]
	v_rsq_f32_e32 v137, v137
	v_pk_fma_f32 v[128:129], v[128:129], s[0:1], v[186:187] op_sel_hi:[1,0,0]
	v_mul_f32_e32 v124, v120, v124
	v_mov_b32_e32 v120, v125
	v_pk_mul_f32 v[120:121], v[120:121], v[176:177] op_sel_hi:[1,0]
	v_mul_f32_e32 v138, 0x45800000, v137
	v_mul_f32_e32 v121, v120, v121
	v_mul_f32_e32 v120, 0xbfb8aa3b, v120
	v_exp_f32_e32 v120, v120
	v_cndmask_b32_e64 v138, v137, v138, s[4:5]
	v_mul_f32_e32 v130, 0x4b800000, v129
	v_cmp_gt_f32_e64 s[4:5], s10, v129
	v_add_f32_e32 v120, 1.0, v120
	v_rcp_f32_e32 v120, v120
	v_cndmask_b32_e64 v129, v129, v130, s[4:5]
	v_rsq_f32_e32 v129, v129
	s_lshl_b32 s0, s33, 7
	v_mul_f32_e32 v125, v121, v120
	v_mov_b32_e32 v120, v126
	v_mov_b32_e32 v121, v122
	v_pk_mul_f32 v[120:121], v[120:121], v[176:177] op_sel_hi:[1,0]
	v_mov_b32_e32 v122, v127
	v_mul_f32_e32 v121, v120, v121
	v_mul_f32_e32 v120, 0xbfb8aa3b, v120
	v_exp_f32_e32 v120, v120
	v_mul_f32_e32 v130, 0x45800000, v129
	s_ashr_i32 s1, s0, 31
	v_cndmask_b32_e64 v130, v129, v130, s[4:5]
	v_add_f32_e32 v120, 1.0, v120
	v_rcp_f32_e32 v120, v120
	s_lshl_b64 s[0:1], s[0:1], 1
	v_rsq_f32_e32 v157, v157
	v_mul_f32_e32 v137, 0x4b800000, v136
	v_mul_f32_e32 v126, v121, v120
	v_pk_mul_f32 v[120:121], v[122:123], v[176:177] op_sel_hi:[1,0]
	v_mul_f32_e32 v159, 0x45800000, v157
	v_mul_f32_e32 v121, v120, v121
	v_mul_f32_e32 v120, 0xbfb8aa3b, v120
	v_exp_f32_e32 v120, v120
	v_cndmask_b32_e32 v168, v157, v159, vcc
	v_cmp_gt_f32_e32 vcc, s10, v136
	v_mul_f32_e32 v129, 0x4b800000, v128
	v_add_f32_e32 v120, 1.0, v120
	v_rcp_f32_e32 v120, v120
	v_cndmask_b32_e32 v136, v136, v137, vcc
	v_rsq_f32_e32 v136, v136
	v_mul_f32_e32 v122, v121, v120
	v_mov_b32_e32 v120, v116
	v_mov_b32_e32 v121, v112
	v_pk_mul_f32 v[120:121], v[120:121], v[176:177] op_sel_hi:[1,0]
	v_mul_f32_e32 v137, 0x45800000, v136
	v_mul_f32_e32 v116, 0xbfb8aa3b, v120
	v_exp_f32_e32 v116, v116
	v_mul_f32_e32 v112, v120, v121
	v_cndmask_b32_e32 v136, v136, v137, vcc
	v_cmp_gt_f32_e32 vcc, s10, v128
	v_add_f32_e32 v116, 1.0, v116
	v_rcp_f32_e32 v116, v116
	v_cndmask_b32_e32 v128, v128, v129, vcc
	v_rsq_f32_e32 v128, v128
	v_mul_f32_e32 v116, v112, v116
	v_mov_b32_e32 v112, v117
	v_pk_mul_f32 v[112:113], v[112:113], v[176:177] op_sel_hi:[1,0]
	v_mul_f32_e32 v129, 0x45800000, v128
	v_mul_f32_e32 v113, v112, v113
	v_mul_f32_e32 v112, 0xbfb8aa3b, v112
	v_exp_f32_e32 v112, v112
	v_cndmask_b32_e32 v128, v128, v129, vcc
	s_andn2_b64 vcc, exec, s[38:39]
	v_add_f32_e32 v112, 1.0, v112
	v_rcp_f32_e32 v112, v112
	s_nop 0
	v_mul_f32_e32 v117, v113, v112
	v_mov_b32_e32 v112, v118
	v_mov_b32_e32 v113, v114
	v_pk_mul_f32 v[112:113], v[112:113], v[176:177] op_sel_hi:[1,0]
	v_mov_b32_e32 v114, v119
	v_mul_f32_e32 v113, v112, v113
	v_mul_f32_e32 v112, 0xbfb8aa3b, v112
	v_exp_f32_e32 v112, v112
	s_nop 0
	v_add_f32_e32 v112, 1.0, v112
	v_rcp_f32_e32 v112, v112
	s_nop 0
	v_mul_f32_e32 v118, v113, v112
	v_pk_mul_f32 v[112:113], v[114:115], v[176:177] op_sel_hi:[1,0]
	v_cvt_pk_bf16_f32 v114, v124, v125
	v_cvt_pk_bf16_f32 v115, v126, v122
	v_cvt_pk_bf16_f32 v116, v116, v117
	v_and_b32_e32 v176, 48, v188
	v_mul_f32_e32 v113, v112, v113
	v_mul_f32_e32 v112, 0xbfb8aa3b, v112
	v_exp_f32_e32 v112, v112
	s_nop 0
	v_add_f32_e32 v112, 1.0, v112
	v_rcp_f32_e32 v112, v112
	s_nop 0
	v_mul_f32_e32 v112, v113, v112
	v_cvt_pk_bf16_f32 v117, v118, v112
	v_mov_b64_e32 v[112:113], s[42:43]
	v_mad_i64_i32 v[118:119], s[4:5], v184, s8, v[112:113]
	v_lshl_add_u64 v[118:119], v[118:119], 0, s[0:1]
	v_lshl_add_u64 v[118:119], v[118:119], 0, s[94:95]
	v_lshl_add_u64 v[118:119], v[118:119], 0, v[176:177]
	global_store_dwordx4 v[118:119], v[114:117], off nt
	s_nop 1
	v_mov_b32_e32 v114, v108
	v_mov_b32_e32 v115, v104
	v_pk_mul_f32 v[114:115], v[114:115], v[174:175] op_sel_hi:[1,0]
	s_nop 0
	v_mul_f32_e32 v108, 0xbfb8aa3b, v114
	v_exp_f32_e32 v108, v108
	v_mul_f32_e32 v104, v114, v115
	v_add_f32_e32 v108, 1.0, v108
	v_rcp_f32_e32 v108, v108
	s_nop 0
	v_mul_f32_e32 v108, v104, v108
	v_mov_b32_e32 v104, v109
	v_pk_mul_f32 v[104:105], v[104:105], v[174:175] op_sel_hi:[1,0]
	s_nop 0
	v_mul_f32_e32 v105, v104, v105
	v_mul_f32_e32 v104, 0xbfb8aa3b, v104
	v_exp_f32_e32 v104, v104
	s_nop 0
	v_add_f32_e32 v104, 1.0, v104
	v_rcp_f32_e32 v104, v104
	s_nop 0
	v_mul_f32_e32 v109, v105, v104
	v_mov_b32_e32 v104, v110
	v_mov_b32_e32 v105, v106
	v_pk_mul_f32 v[104:105], v[104:105], v[174:175] op_sel_hi:[1,0]
	v_mov_b32_e32 v106, v111
	v_mul_f32_e32 v105, v104, v105
	v_mul_f32_e32 v104, 0xbfb8aa3b, v104
	v_exp_f32_e32 v104, v104
	s_nop 0
	v_add_f32_e32 v104, 1.0, v104
	v_rcp_f32_e32 v104, v104
	s_nop 0
	v_mul_f32_e32 v110, v105, v104
	v_pk_mul_f32 v[104:105], v[106:107], v[174:175] op_sel_hi:[1,0]
	s_nop 0
	v_mul_f32_e32 v105, v104, v105
	v_mul_f32_e32 v104, 0xbfb8aa3b, v104
	v_exp_f32_e32 v104, v104
	s_nop 0
	v_add_f32_e32 v104, 1.0, v104
	v_rcp_f32_e32 v104, v104
	s_nop 0
	v_mul_f32_e32 v106, v105, v104
	v_mov_b32_e32 v104, v100
	v_mov_b32_e32 v105, v96
	v_pk_mul_f32 v[104:105], v[104:105], v[174:175] op_sel_hi:[1,0]
	s_nop 0
	v_mul_f32_e32 v100, 0xbfb8aa3b, v104
	v_exp_f32_e32 v100, v100
	v_mul_f32_e32 v96, v104, v105
	v_add_f32_e32 v100, 1.0, v100
	v_rcp_f32_e32 v100, v100
	s_nop 0
	v_mul_f32_e32 v100, v96, v100
	v_mov_b32_e32 v96, v101
	v_pk_mul_f32 v[96:97], v[96:97], v[174:175] op_sel_hi:[1,0]
	s_nop 0
	v_mul_f32_e32 v97, v96, v97
	v_mul_f32_e32 v96, 0xbfb8aa3b, v96
	v_exp_f32_e32 v96, v96
	s_nop 0
	v_add_f32_e32 v96, 1.0, v96
	v_rcp_f32_e32 v96, v96
	s_nop 0
	v_mul_f32_e32 v101, v97, v96
	v_mov_b32_e32 v96, v102
	v_mov_b32_e32 v97, v98
	v_pk_mul_f32 v[96:97], v[96:97], v[174:175] op_sel_hi:[1,0]
	v_mov_b32_e32 v98, v103
	v_mul_f32_e32 v97, v96, v97
	v_mul_f32_e32 v96, 0xbfb8aa3b, v96
	v_exp_f32_e32 v96, v96
	s_nop 0
	v_add_f32_e32 v96, 1.0, v96
	v_rcp_f32_e32 v96, v96
	s_nop 0
	v_mul_f32_e32 v102, v97, v96
	v_pk_mul_f32 v[96:97], v[98:99], v[174:175] op_sel_hi:[1,0]
	s_nop 0
	v_mul_f32_e32 v97, v96, v97
	v_mul_f32_e32 v96, 0xbfb8aa3b, v96
	v_exp_f32_e32 v96, v96
	s_nop 0
	v_add_f32_e32 v96, 1.0, v96
	v_rcp_f32_e32 v96, v96
	s_nop 0
	v_mul_f32_e32 v99, v97, v96
	v_cvt_pk_bf16_f32 v96, v108, v109
	v_cvt_pk_bf16_f32 v97, v110, v106
	v_cvt_pk_bf16_f32 v98, v100, v101
	v_mad_i64_i32 v[100:101], s[2:3], v170, s8, v[112:113]
	v_lshl_add_u64 v[100:101], v[100:101], 0, s[0:1]
	v_lshl_add_u64 v[100:101], v[100:101], 0, s[94:95]
	v_lshl_add_u64 v[100:101], v[100:101], 0, v[176:177]
	v_cvt_pk_bf16_f32 v99, v102, v99
	global_store_dwordx4 v[100:101], v[96:99], off nt
	s_nop 1
	v_mov_b32_e32 v96, v92
	v_mov_b32_e32 v97, v88
	v_pk_mul_f32 v[96:97], v[96:97], v[172:173] op_sel_hi:[1,0]
	s_nop 0
	v_mul_f32_e32 v92, 0xbfb8aa3b, v96
	v_exp_f32_e32 v92, v92
	v_mul_f32_e32 v88, v96, v97
	v_add_f32_e32 v92, 1.0, v92
	v_rcp_f32_e32 v92, v92
	s_nop 0
	v_mul_f32_e32 v92, v88, v92
	v_mov_b32_e32 v88, v93
	v_pk_mul_f32 v[88:89], v[88:89], v[172:173] op_sel_hi:[1,0]
	s_nop 0
	v_mul_f32_e32 v89, v88, v89
	v_mul_f32_e32 v88, 0xbfb8aa3b, v88
	v_exp_f32_e32 v88, v88
	s_nop 0
	v_add_f32_e32 v88, 1.0, v88
	v_rcp_f32_e32 v88, v88
	s_nop 0
	v_mul_f32_e32 v93, v89, v88
	v_mov_b32_e32 v88, v94
	v_mov_b32_e32 v89, v90
	v_pk_mul_f32 v[88:89], v[88:89], v[172:173] op_sel_hi:[1,0]
	v_mov_b32_e32 v90, v95
	v_mul_f32_e32 v89, v88, v89
	v_mul_f32_e32 v88, 0xbfb8aa3b, v88
	v_exp_f32_e32 v88, v88
	s_nop 0
	v_add_f32_e32 v88, 1.0, v88
	v_rcp_f32_e32 v88, v88
	s_nop 0
	v_mul_f32_e32 v94, v89, v88
	v_pk_mul_f32 v[88:89], v[90:91], v[172:173] op_sel_hi:[1,0]
	s_nop 0
	v_mul_f32_e32 v89, v88, v89
	v_mul_f32_e32 v88, 0xbfb8aa3b, v88
	v_exp_f32_e32 v88, v88
	s_nop 0
	v_add_f32_e32 v88, 1.0, v88
	v_rcp_f32_e32 v88, v88
	s_nop 0
	v_mul_f32_e32 v90, v89, v88
	v_mov_b32_e32 v88, v84
	v_mov_b32_e32 v89, v80
	v_pk_mul_f32 v[88:89], v[88:89], v[172:173] op_sel_hi:[1,0]
	s_nop 0
	v_mul_f32_e32 v84, 0xbfb8aa3b, v88
	v_exp_f32_e32 v84, v84
	v_mul_f32_e32 v80, v88, v89
	v_add_f32_e32 v84, 1.0, v84
	v_rcp_f32_e32 v84, v84
	s_nop 0
	v_mul_f32_e32 v84, v80, v84
	v_mov_b32_e32 v80, v85
	v_pk_mul_f32 v[80:81], v[80:81], v[172:173] op_sel_hi:[1,0]
	s_nop 0
	v_mul_f32_e32 v81, v80, v81
	v_mul_f32_e32 v80, 0xbfb8aa3b, v80
	v_exp_f32_e32 v80, v80
	s_nop 0
	v_add_f32_e32 v80, 1.0, v80
	v_rcp_f32_e32 v80, v80
	s_nop 0
	v_mul_f32_e32 v85, v81, v80
	v_mov_b32_e32 v80, v86
	v_mov_b32_e32 v81, v82
	v_pk_mul_f32 v[80:81], v[80:81], v[172:173] op_sel_hi:[1,0]
	v_mov_b32_e32 v82, v87
	v_mul_f32_e32 v81, v80, v81
	v_mul_f32_e32 v80, 0xbfb8aa3b, v80
	v_exp_f32_e32 v80, v80
	s_nop 0
	v_add_f32_e32 v80, 1.0, v80
	v_rcp_f32_e32 v80, v80
	s_nop 0
	v_mul_f32_e32 v86, v81, v80
	v_pk_mul_f32 v[80:81], v[82:83], v[172:173] op_sel_hi:[1,0]
	s_nop 0
	v_mul_f32_e32 v81, v80, v81
	v_mul_f32_e32 v80, 0xbfb8aa3b, v80
	v_exp_f32_e32 v80, v80
	s_nop 0
	v_add_f32_e32 v80, 1.0, v80
	v_rcp_f32_e32 v80, v80
	s_nop 0
	v_mul_f32_e32 v83, v81, v80
	v_cvt_pk_bf16_f32 v80, v92, v93
	v_cvt_pk_bf16_f32 v81, v94, v90
	v_cvt_pk_bf16_f32 v82, v84, v85
	v_mad_i64_i32 v[84:85], s[2:3], v166, s8, v[112:113]
	v_lshl_add_u64 v[84:85], v[84:85], 0, s[0:1]
	v_lshl_add_u64 v[84:85], v[84:85], 0, s[94:95]
	v_lshl_add_u64 v[84:85], v[84:85], 0, v[176:177]
	v_cvt_pk_bf16_f32 v83, v86, v83
	global_store_dwordx4 v[84:85], v[80:83], off nt
	s_nop 1
	v_mov_b32_e32 v80, v76
	v_mov_b32_e32 v81, v72
	v_pk_mul_f32 v[80:81], v[80:81], v[168:169] op_sel_hi:[1,0]
	s_nop 0
	v_mul_f32_e32 v76, 0xbfb8aa3b, v80
	v_exp_f32_e32 v76, v76
	v_mul_f32_e32 v72, v80, v81
	v_add_f32_e32 v76, 1.0, v76
	v_rcp_f32_e32 v76, v76
	s_nop 0
	v_mul_f32_e32 v76, v72, v76
	v_mov_b32_e32 v72, v77
	v_pk_mul_f32 v[72:73], v[72:73], v[168:169] op_sel_hi:[1,0]
	s_nop 0
	v_mul_f32_e32 v73, v72, v73
	v_mul_f32_e32 v72, 0xbfb8aa3b, v72
	v_exp_f32_e32 v72, v72
	s_nop 0
	v_add_f32_e32 v72, 1.0, v72
	v_rcp_f32_e32 v72, v72
	s_nop 0
	v_mul_f32_e32 v77, v73, v72
	v_mov_b32_e32 v72, v78
	v_mov_b32_e32 v73, v74
	v_pk_mul_f32 v[72:73], v[72:73], v[168:169] op_sel_hi:[1,0]
	v_mov_b32_e32 v74, v79
	v_mul_f32_e32 v73, v72, v73
	v_mul_f32_e32 v72, 0xbfb8aa3b, v72
	v_exp_f32_e32 v72, v72
	s_nop 0
	v_add_f32_e32 v72, 1.0, v72
	v_rcp_f32_e32 v72, v72
	s_nop 0
	v_mul_f32_e32 v78, v73, v72
	v_pk_mul_f32 v[72:73], v[74:75], v[168:169] op_sel_hi:[1,0]
	s_nop 0
	v_mul_f32_e32 v73, v72, v73
	v_mul_f32_e32 v72, 0xbfb8aa3b, v72
	v_exp_f32_e32 v72, v72
	s_nop 0
	v_add_f32_e32 v72, 1.0, v72
	v_rcp_f32_e32 v72, v72
	s_nop 0
	v_mul_f32_e32 v74, v73, v72
	v_mov_b32_e32 v72, v68
	v_mov_b32_e32 v73, v64
	v_pk_mul_f32 v[72:73], v[72:73], v[168:169] op_sel_hi:[1,0]
	s_nop 0
	v_mul_f32_e32 v68, 0xbfb8aa3b, v72
	v_exp_f32_e32 v68, v68
	v_mul_f32_e32 v64, v72, v73
	v_add_f32_e32 v68, 1.0, v68
	v_rcp_f32_e32 v68, v68
	s_nop 0
	v_mul_f32_e32 v68, v64, v68
	v_mov_b32_e32 v64, v69
	v_pk_mul_f32 v[64:65], v[64:65], v[168:169] op_sel_hi:[1,0]
	s_nop 0
	v_mul_f32_e32 v65, v64, v65
	v_mul_f32_e32 v64, 0xbfb8aa3b, v64
	v_exp_f32_e32 v64, v64
	s_nop 0
	v_add_f32_e32 v64, 1.0, v64
	v_rcp_f32_e32 v64, v64
	s_nop 0
	v_mul_f32_e32 v69, v65, v64
	v_mov_b32_e32 v64, v70
	v_mov_b32_e32 v65, v66
	v_pk_mul_f32 v[64:65], v[64:65], v[168:169] op_sel_hi:[1,0]
	v_mov_b32_e32 v66, v71
	v_mul_f32_e32 v65, v64, v65
	v_mul_f32_e32 v64, 0xbfb8aa3b, v64
	v_exp_f32_e32 v64, v64
	s_nop 0
	v_add_f32_e32 v64, 1.0, v64
	v_rcp_f32_e32 v64, v64
	s_nop 0
	v_mul_f32_e32 v70, v65, v64
	v_pk_mul_f32 v[64:65], v[66:67], v[168:169] op_sel_hi:[1,0]
	s_nop 0
	v_mul_f32_e32 v65, v64, v65
	v_mul_f32_e32 v64, 0xbfb8aa3b, v64
	v_exp_f32_e32 v64, v64
	s_nop 0
	v_add_f32_e32 v64, 1.0, v64
	v_rcp_f32_e32 v64, v64
	s_nop 0
	v_mul_f32_e32 v67, v65, v64
	v_cvt_pk_bf16_f32 v64, v76, v77
	v_cvt_pk_bf16_f32 v65, v78, v74
	v_cvt_pk_bf16_f32 v66, v68, v69
	v_mad_i64_i32 v[68:69], s[2:3], v164, s8, v[112:113]
	v_lshl_add_u64 v[68:69], v[68:69], 0, s[0:1]
	v_lshl_add_u64 v[68:69], v[68:69], 0, s[94:95]
	v_lshl_add_u64 v[68:69], v[68:69], 0, v[176:177]
	v_cvt_pk_bf16_f32 v67, v70, v67
	global_store_dwordx4 v[68:69], v[64:67], off nt
	s_nop 1
	v_mov_b32_e32 v64, v60
	v_mov_b32_e32 v65, v56
	v_pk_mul_f32 v[64:65], v[64:65], v[138:139] op_sel_hi:[1,0]
	s_nop 0
	v_mul_f32_e32 v60, 0xbfb8aa3b, v64
	v_exp_f32_e32 v60, v60
	v_mul_f32_e32 v56, v64, v65
	v_add_f32_e32 v60, 1.0, v60
	v_rcp_f32_e32 v60, v60
	s_nop 0
	v_mul_f32_e32 v60, v56, v60
	v_mov_b32_e32 v56, v61
	v_pk_mul_f32 v[56:57], v[56:57], v[138:139] op_sel_hi:[1,0]
	s_nop 0
	v_mul_f32_e32 v57, v56, v57
	v_mul_f32_e32 v56, 0xbfb8aa3b, v56
	v_exp_f32_e32 v56, v56
	s_nop 0
	v_add_f32_e32 v56, 1.0, v56
	v_rcp_f32_e32 v56, v56
	s_nop 0
	v_mul_f32_e32 v61, v57, v56
	v_mov_b32_e32 v56, v62
	v_mov_b32_e32 v57, v58
	v_pk_mul_f32 v[56:57], v[56:57], v[138:139] op_sel_hi:[1,0]
	v_mov_b32_e32 v58, v63
	v_mul_f32_e32 v57, v56, v57
	v_mul_f32_e32 v56, 0xbfb8aa3b, v56
	v_exp_f32_e32 v56, v56
	s_nop 0
	v_add_f32_e32 v56, 1.0, v56
	v_rcp_f32_e32 v56, v56
	s_nop 0
	v_mul_f32_e32 v62, v57, v56
	v_pk_mul_f32 v[56:57], v[58:59], v[138:139] op_sel_hi:[1,0]
	s_nop 0
	v_mul_f32_e32 v57, v56, v57
	v_mul_f32_e32 v56, 0xbfb8aa3b, v56
	v_exp_f32_e32 v56, v56
	s_nop 0
	v_add_f32_e32 v56, 1.0, v56
	v_rcp_f32_e32 v56, v56
	s_nop 0
	v_mul_f32_e32 v58, v57, v56
	v_mov_b32_e32 v56, v52
	v_mov_b32_e32 v57, v48
	v_pk_mul_f32 v[56:57], v[56:57], v[138:139] op_sel_hi:[1,0]
	s_nop 0
	v_mul_f32_e32 v52, 0xbfb8aa3b, v56
	v_exp_f32_e32 v52, v52
	v_mul_f32_e32 v48, v56, v57
	v_add_f32_e32 v52, 1.0, v52
	v_rcp_f32_e32 v52, v52
	s_nop 0
	v_mul_f32_e32 v52, v48, v52
	v_mov_b32_e32 v48, v53
	v_pk_mul_f32 v[48:49], v[48:49], v[138:139] op_sel_hi:[1,0]
	s_nop 0
	v_mul_f32_e32 v49, v48, v49
	v_mul_f32_e32 v48, 0xbfb8aa3b, v48
	v_exp_f32_e32 v48, v48
	s_nop 0
	v_add_f32_e32 v48, 1.0, v48
	v_rcp_f32_e32 v48, v48
	s_nop 0
	v_mul_f32_e32 v53, v49, v48
	v_mov_b32_e32 v48, v54
	v_mov_b32_e32 v49, v50
	v_pk_mul_f32 v[48:49], v[48:49], v[138:139] op_sel_hi:[1,0]
	v_mov_b32_e32 v50, v55
	v_mul_f32_e32 v49, v48, v49
	v_mul_f32_e32 v48, 0xbfb8aa3b, v48
	v_exp_f32_e32 v48, v48
	s_nop 0
	v_add_f32_e32 v48, 1.0, v48
	v_rcp_f32_e32 v48, v48
	s_nop 0
	v_mul_f32_e32 v54, v49, v48
	v_pk_mul_f32 v[48:49], v[50:51], v[138:139] op_sel_hi:[1,0]
	s_nop 0
	v_mul_f32_e32 v49, v48, v49
	v_mul_f32_e32 v48, 0xbfb8aa3b, v48
	v_exp_f32_e32 v48, v48
	s_nop 0
	v_add_f32_e32 v48, 1.0, v48
	v_rcp_f32_e32 v48, v48
	s_nop 0
	v_mul_f32_e32 v51, v49, v48
	v_cvt_pk_bf16_f32 v48, v60, v61
	v_cvt_pk_bf16_f32 v49, v62, v58
	v_cvt_pk_bf16_f32 v50, v52, v53
	v_mad_i64_i32 v[52:53], s[2:3], v162, s8, v[112:113]
	v_lshl_add_u64 v[52:53], v[52:53], 0, s[0:1]
	v_lshl_add_u64 v[52:53], v[52:53], 0, s[94:95]
	v_lshl_add_u64 v[52:53], v[52:53], 0, v[176:177]
	v_cvt_pk_bf16_f32 v51, v54, v51
	global_store_dwordx4 v[52:53], v[48:51], off nt
	s_nop 1
	v_mov_b32_e32 v48, v44
	v_mov_b32_e32 v49, v40
	v_pk_mul_f32 v[48:49], v[48:49], v[136:137] op_sel_hi:[1,0]
	s_nop 0
	v_mul_f32_e32 v44, 0xbfb8aa3b, v48
	v_exp_f32_e32 v44, v44
	v_mul_f32_e32 v40, v48, v49
	v_add_f32_e32 v44, 1.0, v44
	v_rcp_f32_e32 v44, v44
	s_nop 0
	v_mul_f32_e32 v44, v40, v44
	v_mov_b32_e32 v40, v45
	v_pk_mul_f32 v[40:41], v[40:41], v[136:137] op_sel_hi:[1,0]
	s_nop 0
	v_mul_f32_e32 v41, v40, v41
	v_mul_f32_e32 v40, 0xbfb8aa3b, v40
	v_exp_f32_e32 v40, v40
	s_nop 0
	v_add_f32_e32 v40, 1.0, v40
	v_rcp_f32_e32 v40, v40
	s_nop 0
	v_mul_f32_e32 v45, v41, v40
	v_mov_b32_e32 v40, v46
	v_mov_b32_e32 v41, v42
	v_pk_mul_f32 v[40:41], v[40:41], v[136:137] op_sel_hi:[1,0]
	v_mov_b32_e32 v42, v47
	v_mul_f32_e32 v41, v40, v41
	v_mul_f32_e32 v40, 0xbfb8aa3b, v40
	v_exp_f32_e32 v40, v40
	s_nop 0
	v_add_f32_e32 v40, 1.0, v40
	v_rcp_f32_e32 v40, v40
	s_nop 0
	v_mul_f32_e32 v46, v41, v40
	v_pk_mul_f32 v[40:41], v[42:43], v[136:137] op_sel_hi:[1,0]
	s_nop 0
	v_mul_f32_e32 v41, v40, v41
	v_mul_f32_e32 v40, 0xbfb8aa3b, v40
	v_exp_f32_e32 v40, v40
	s_nop 0
	v_add_f32_e32 v40, 1.0, v40
	v_rcp_f32_e32 v40, v40
	s_nop 0
	v_mul_f32_e32 v42, v41, v40
	v_mov_b32_e32 v40, v36
	v_mov_b32_e32 v41, v32
	v_pk_mul_f32 v[40:41], v[40:41], v[136:137] op_sel_hi:[1,0]
	s_nop 0
	v_mul_f32_e32 v36, 0xbfb8aa3b, v40
	v_exp_f32_e32 v36, v36
	v_mul_f32_e32 v32, v40, v41
	v_add_f32_e32 v36, 1.0, v36
	v_rcp_f32_e32 v36, v36
	s_nop 0
	v_mul_f32_e32 v36, v32, v36
	v_mov_b32_e32 v32, v37
	v_pk_mul_f32 v[32:33], v[32:33], v[136:137] op_sel_hi:[1,0]
	s_nop 0
	v_mul_f32_e32 v33, v32, v33
	v_mul_f32_e32 v32, 0xbfb8aa3b, v32
	v_exp_f32_e32 v32, v32
	s_nop 0
	v_add_f32_e32 v32, 1.0, v32
	v_rcp_f32_e32 v32, v32
	s_nop 0
	v_mul_f32_e32 v37, v33, v32
	v_mov_b32_e32 v32, v38
	v_mov_b32_e32 v33, v34
	v_pk_mul_f32 v[32:33], v[32:33], v[136:137] op_sel_hi:[1,0]
	v_mov_b32_e32 v34, v39
	v_mul_f32_e32 v33, v32, v33
	v_mul_f32_e32 v32, 0xbfb8aa3b, v32
	v_exp_f32_e32 v32, v32
	s_nop 0
	v_add_f32_e32 v32, 1.0, v32
	v_rcp_f32_e32 v32, v32
	s_nop 0
	v_mul_f32_e32 v38, v33, v32
	v_pk_mul_f32 v[32:33], v[34:35], v[136:137] op_sel_hi:[1,0]
	s_nop 0
	v_mul_f32_e32 v33, v32, v33
	v_mul_f32_e32 v32, 0xbfb8aa3b, v32
	v_exp_f32_e32 v32, v32
	s_nop 0
	v_add_f32_e32 v32, 1.0, v32
	v_rcp_f32_e32 v32, v32
	s_nop 0
	v_mul_f32_e32 v35, v33, v32
	v_cvt_pk_bf16_f32 v32, v44, v45
	v_cvt_pk_bf16_f32 v33, v46, v42
	v_cvt_pk_bf16_f32 v34, v36, v37
	v_mad_i64_i32 v[36:37], s[2:3], v160, s8, v[112:113]
	v_lshl_add_u64 v[36:37], v[36:37], 0, s[0:1]
	v_lshl_add_u64 v[36:37], v[36:37], 0, s[94:95]
	v_lshl_add_u64 v[36:37], v[36:37], 0, v[176:177]
	v_cvt_pk_bf16_f32 v35, v38, v35
	global_store_dwordx4 v[36:37], v[32:35], off nt
	s_nop 1
	v_mov_b32_e32 v32, v28
	v_mov_b32_e32 v33, v24
	v_pk_mul_f32 v[32:33], v[32:33], v[130:131] op_sel_hi:[1,0]
	s_nop 0
	v_mul_f32_e32 v28, 0xbfb8aa3b, v32
	v_exp_f32_e32 v28, v28
	v_mul_f32_e32 v24, v32, v33
	v_add_f32_e32 v28, 1.0, v28
	v_rcp_f32_e32 v28, v28
	s_nop 0
	v_mul_f32_e32 v28, v24, v28
	v_mov_b32_e32 v24, v29
	v_pk_mul_f32 v[24:25], v[24:25], v[130:131] op_sel_hi:[1,0]
	s_nop 0
	v_mul_f32_e32 v25, v24, v25
	v_mul_f32_e32 v24, 0xbfb8aa3b, v24
	v_exp_f32_e32 v24, v24
	s_nop 0
	v_add_f32_e32 v24, 1.0, v24
	v_rcp_f32_e32 v24, v24
	s_nop 0
	v_mul_f32_e32 v29, v25, v24
	v_mov_b32_e32 v24, v30
	v_mov_b32_e32 v25, v26
	v_pk_mul_f32 v[24:25], v[24:25], v[130:131] op_sel_hi:[1,0]
	v_mov_b32_e32 v26, v31
	v_mul_f32_e32 v25, v24, v25
	v_mul_f32_e32 v24, 0xbfb8aa3b, v24
	v_exp_f32_e32 v24, v24
	s_nop 0
	v_add_f32_e32 v24, 1.0, v24
	v_rcp_f32_e32 v24, v24
	s_nop 0
	v_mul_f32_e32 v30, v25, v24
	v_pk_mul_f32 v[24:25], v[26:27], v[130:131] op_sel_hi:[1,0]
	s_nop 0
	v_mul_f32_e32 v25, v24, v25
	v_mul_f32_e32 v24, 0xbfb8aa3b, v24
	v_exp_f32_e32 v24, v24
	s_nop 0
	v_add_f32_e32 v24, 1.0, v24
	v_rcp_f32_e32 v24, v24
	s_nop 0
	v_mul_f32_e32 v26, v25, v24
	v_mov_b32_e32 v24, v20
	v_mov_b32_e32 v25, v16
	v_pk_mul_f32 v[24:25], v[24:25], v[130:131] op_sel_hi:[1,0]
	s_nop 0
	v_mul_f32_e32 v20, 0xbfb8aa3b, v24
	v_exp_f32_e32 v20, v20
	v_mul_f32_e32 v16, v24, v25
	v_add_f32_e32 v20, 1.0, v20
	v_rcp_f32_e32 v20, v20
	s_nop 0
	v_mul_f32_e32 v20, v16, v20
	v_mov_b32_e32 v16, v21
	v_pk_mul_f32 v[16:17], v[16:17], v[130:131] op_sel_hi:[1,0]
	s_nop 0
	v_mul_f32_e32 v17, v16, v17
	v_mul_f32_e32 v16, 0xbfb8aa3b, v16
	v_exp_f32_e32 v16, v16
	s_nop 0
	v_add_f32_e32 v16, 1.0, v16
	v_rcp_f32_e32 v16, v16
	s_nop 0
	v_mul_f32_e32 v21, v17, v16
	v_mov_b32_e32 v16, v22
	v_mov_b32_e32 v17, v18
	v_pk_mul_f32 v[16:17], v[16:17], v[130:131] op_sel_hi:[1,0]
	v_mov_b32_e32 v18, v23
	v_mul_f32_e32 v17, v16, v17
	v_mul_f32_e32 v16, 0xbfb8aa3b, v16
	v_exp_f32_e32 v16, v16
	s_nop 0
	v_add_f32_e32 v16, 1.0, v16
	v_rcp_f32_e32 v16, v16
	s_nop 0
	v_mul_f32_e32 v22, v17, v16
	v_pk_mul_f32 v[16:17], v[18:19], v[130:131] op_sel_hi:[1,0]
	s_nop 0
	v_mul_f32_e32 v17, v16, v17
	v_mul_f32_e32 v16, 0xbfb8aa3b, v16
	v_exp_f32_e32 v16, v16
	s_nop 0
	v_add_f32_e32 v16, 1.0, v16
	v_rcp_f32_e32 v16, v16
	s_nop 0
	v_mul_f32_e32 v19, v17, v16
	v_cvt_pk_bf16_f32 v16, v28, v29
	v_cvt_pk_bf16_f32 v17, v30, v26
	v_cvt_pk_bf16_f32 v18, v20, v21
	v_mad_i64_i32 v[20:21], s[2:3], v158, s8, v[112:113]
	v_lshl_add_u64 v[20:21], v[20:21], 0, s[0:1]
	v_lshl_add_u64 v[20:21], v[20:21], 0, s[94:95]
	v_lshl_add_u64 v[20:21], v[20:21], 0, v[176:177]
	v_cvt_pk_bf16_f32 v19, v22, v19
	global_store_dwordx4 v[20:21], v[16:19], off nt
	s_nop 1
	v_mov_b32_e32 v16, v12
	v_mov_b32_e32 v17, v8
	v_pk_mul_f32 v[16:17], v[16:17], v[128:129] op_sel_hi:[1,0]
	s_nop 0
	v_mul_f32_e32 v12, 0xbfb8aa3b, v16
	v_exp_f32_e32 v12, v12
	v_mul_f32_e32 v8, v16, v17
	v_add_f32_e32 v12, 1.0, v12
	v_rcp_f32_e32 v12, v12
	s_nop 0
	v_mul_f32_e32 v12, v8, v12
	v_mov_b32_e32 v8, v13
	v_pk_mul_f32 v[8:9], v[8:9], v[128:129] op_sel_hi:[1,0]
	s_nop 0
	v_mul_f32_e32 v9, v8, v9
	v_mul_f32_e32 v8, 0xbfb8aa3b, v8
	v_exp_f32_e32 v8, v8
	s_nop 0
	v_add_f32_e32 v8, 1.0, v8
	v_rcp_f32_e32 v8, v8
	s_nop 0
	v_mul_f32_e32 v13, v9, v8
	v_mov_b32_e32 v8, v14
	v_mov_b32_e32 v9, v10
	v_pk_mul_f32 v[8:9], v[8:9], v[128:129] op_sel_hi:[1,0]
	v_mov_b32_e32 v10, v15
	v_mul_f32_e32 v9, v8, v9
	v_mul_f32_e32 v8, 0xbfb8aa3b, v8
	v_exp_f32_e32 v8, v8
	s_nop 0
	v_add_f32_e32 v8, 1.0, v8
	v_rcp_f32_e32 v8, v8
	s_nop 0
	v_mul_f32_e32 v14, v9, v8
	v_pk_mul_f32 v[8:9], v[10:11], v[128:129] op_sel_hi:[1,0]
	s_nop 0
	v_mul_f32_e32 v9, v8, v9
	v_mul_f32_e32 v8, 0xbfb8aa3b, v8
	v_exp_f32_e32 v8, v8
	s_nop 0
	v_add_f32_e32 v8, 1.0, v8
	v_rcp_f32_e32 v8, v8
	s_nop 0
	v_mul_f32_e32 v10, v9, v8
	v_mov_b32_e32 v8, v4
	v_mov_b32_e32 v9, v0
	v_pk_mul_f32 v[8:9], v[8:9], v[128:129] op_sel_hi:[1,0]
	s_nop 0
	v_mul_f32_e32 v4, 0xbfb8aa3b, v8
	v_exp_f32_e32 v4, v4
	v_mul_f32_e32 v0, v8, v9
	v_add_f32_e32 v4, 1.0, v4
	v_rcp_f32_e32 v4, v4
	s_nop 0
	v_mul_f32_e32 v4, v0, v4
	v_mov_b32_e32 v0, v5
	v_pk_mul_f32 v[0:1], v[0:1], v[128:129] op_sel_hi:[1,0]
	s_nop 0
	v_mul_f32_e32 v1, v0, v1
	v_mul_f32_e32 v0, 0xbfb8aa3b, v0
	v_exp_f32_e32 v0, v0
	s_nop 0
	v_add_f32_e32 v0, 1.0, v0
	v_rcp_f32_e32 v0, v0
	s_nop 0
	v_mul_f32_e32 v5, v1, v0
	v_mov_b32_e32 v0, v6
	v_mov_b32_e32 v1, v2
	v_pk_mul_f32 v[0:1], v[0:1], v[128:129] op_sel_hi:[1,0]
	v_mov_b32_e32 v2, v7
	v_mul_f32_e32 v1, v0, v1
	v_mul_f32_e32 v0, 0xbfb8aa3b, v0
	v_exp_f32_e32 v0, v0
	s_nop 0
	v_add_f32_e32 v0, 1.0, v0
	v_rcp_f32_e32 v0, v0
	s_nop 0
	v_mul_f32_e32 v6, v1, v0
	v_pk_mul_f32 v[0:1], v[2:3], v[128:129] op_sel_hi:[1,0]
	s_nop 0
	v_mul_f32_e32 v1, v0, v1
	v_mul_f32_e32 v0, 0xbfb8aa3b, v0
	v_exp_f32_e32 v0, v0
	s_nop 0
	v_add_f32_e32 v0, 1.0, v0
	v_rcp_f32_e32 v0, v0
	s_nop 0
	v_mul_f32_e32 v3, v1, v0
	v_cvt_pk_bf16_f32 v0, v12, v13
	v_cvt_pk_bf16_f32 v1, v14, v10
	v_cvt_pk_bf16_f32 v2, v4, v5
	v_mad_i64_i32 v[4:5], s[2:3], v156, s8, v[112:113]
	v_lshl_add_u64 v[4:5], v[4:5], 0, s[0:1]
	v_lshl_add_u64 v[4:5], v[4:5], 0, s[94:95]
	v_lshl_add_u64 v[4:5], v[4:5], 0, v[176:177]
	s_mov_b64 s[0:1], -1
	v_cvt_pk_bf16_f32 v3, v6, v3
	global_store_dwordx4 v[4:5], v[0:3], off nt
	s_cbranch_vccnz .LBB0_1064
	s_andn2_b64 vcc, exec, s[40:41]
	s_cbranch_vccnz .LBB0_1063
	s_barrier
	s_branch .LBB0_1063
